# gla_post row loop: first-row vmcnt ladder replaced by one pre-loop wait + counted vmcnt(4) at the rotation, next row's 12 loads stay in flight during the row
# baseline (speedup 1.0000x reference)
; #define GAS __attribute__((address_space(1)))
; DI unsigned pk2(float lo, float hi) { f32x2_t v = {lo, hi}; bf16x2_t b = __builtin_convertvector(v, bf16x2_t); return __builtin_bit_cast(unsigned, b); }
; DI float silu_f(float x) { return x * __builtin_amdgcn_rcpf(1.0f + __expf(-x)); }
; DI void phase_gla_post(const Frame& F0, const Args& a, int jl, int nrows) {
;     ...
;     const f32x4 g0 = *(const GAS f32x4*)(a.gla_head_gain + (size_t)jl * HV + F.lane * 8), g1 = *(const GAS f32x4*)(a.gla_head_gain + (size_t)jl * HV + F.lane * 8 + 4);
;     v4u of[4], ob[4], rr[4];
;     const int nfull = nrows / NGW, xr = F.wave * F.G + F.vcu, nit = nfull + (xr < nrows - nfull * NGW ? 1 : 0);
;     ...
;     if (nit > 0) { const int R0 = POST_ROW(0);
; #pragma unroll
;         for (int j = 0; j < 4; ++j) { const size_t off = (size_t)R0 * VD + j * HV + F.lane * 8;
;             of[j] = *(const GAS v4u*)(O + off); ob[j] = *(const GAS v4u*)(O + (size_t)MROWS * VD + off); rr[j] = *(const GAS v4u*)(Rb + off); } }
;     for (int it = 0; it < nit; ++it) { const int R = POST_ROW(it);
;         v4u ofn[4], obn[4], rrn[4]; const int Rn = POST_ROW(it + 1);
;         if (it + 1 < nit) {
; #pragma unroll
;             for (int j = 0; j < 4; ++j) { const size_t off = (size_t)Rn * VD + j * HV + F.lane * 8;
;                 ofn[j] = *(const GAS v4u*)(O + off); obn[j] = *(const GAS v4u*)(O + (size_t)MROWS * VD + off); rrn[j] = *(const GAS v4u*)(Rb + off); } }
;         v4u wout[4];
; #pragma unroll
;         for (int j = 0; j < 4; ++j) {
;             float o[8], r[8];
; #pragma unroll
;             for (int q = 0; q < 4; ++q) { o[2 * q] = bflo(of[j][q]) + bflo(ob[j][q]); o[2 * q + 1] = bfhi(of[j][q]) + bfhi(ob[j][q]); r[2 * q] = bflo(rr[j][q]); r[2 * q + 1] = bfhi(rr[j][q]); }
;             float ss = 0.f;
; #pragma unroll
;             for (int q = 0; q < 8; ++q) ss += o[q] * o[q];
;             const float rs = __builtin_amdgcn_rsqf(wave_sum(ss) * (1.0f / HV) + EPS);
;             float u[8];
; #pragma unroll
;             for (int q = 0; q < 8; ++q) { const float g = q < 4 ? g0[q] : g1[q - 4]; u[q] = o[q] * rs * g * silu_f(r[q]); }
;             wout[j] = (v4u){pk2(u[0], u[1]), pk2(u[2], u[3]), pk2(u[4], u[5]), pk2(u[6], u[7])};
.LBB0_906:
	s_mov_b32 s13, s52
	v_mov_b32_e32 v2, v222
	s_mov_b32 s14, s51
	s_waitcnt vmcnt(0)
	v_mov_b32_e32 v4, v0
	s_mul_i32 s12, s13, s3
	s_add_i32 s12, s12, s14
	s_cmp_lt_i32 s12, s8
	s_cselect_b64 s[16:17], -1, 0
	s_cmp_lg_u64 s[16:17], 0
	s_addc_u32 s10, s6, 0
	s_mov_b64 s[4:5], s[30:31]
	s_cmp_lt_i32 s10, 1
	s_cbranch_scc1 .LBB0_905
	s_add_u32 s40, s4, 0x29a84000
	s_addc_u32 s41, s5, 0
	s_add_u32 s42, s4, 0x207e4000
	s_addc_u32 s43, s5, 0
	s_lshl_b32 s14, s14, 3
	s_add_i32 s15, s14, s13
	s_add_i32 s12, s7, s12
	s_and_b64 s[16:17], s[38:39], exec
	s_cselect_b32 s16, s15, s12
	v_lshlrev_b32_e32 v108, 3, v2
	s_ashr_i32 s17, s16, 31
	v_ashrrev_i32_e32 v109, 31, v108
	s_lshl_b64 s[16:17], s[16:17], 11
	v_lshl_add_u64 v[12:13], s[16:17], 0, v[108:109]
	s_add_u32 s44, s4, 0x2bc84000
	v_lshlrev_b64 v[12:13], 1, v[12:13]
	v_lshl_add_u64 v[8:9], v[108:109], 2, s[0:1]
	s_addc_u32 s45, s5, 0
	v_lshl_add_u64 v[14:15], s[40:41], 0, v[12:13]
	global_load_dwordx4 v[4:7], v[8:9], off nt
	s_nop 0
	global_load_dwordx4 v[8:11], v[8:9], off offset:16 nt
	v_lshl_add_u64 v[16:17], s[44:45], 0, v[12:13]
	v_lshl_add_u64 v[12:13], s[42:43], 0, v[12:13]
	global_load_dwordx4 v[104:107], v[14:15], off nt
	global_load_dwordx4 v[96:99], v[14:15], off offset:1024 nt
	global_load_dwordx4 v[100:103], v[16:17], off nt
	global_load_dwordx4 v[92:95], v[16:17], off offset:1024 nt
	global_load_dwordx4 v[84:87], v[12:13], off nt
	global_load_dwordx4 v[88:91], v[12:13], off offset:1024 nt
	global_load_dwordx4 v[80:83], v[14:15], off offset:2048 nt
	global_load_dwordx4 v[68:71], v[14:15], off offset:3072 nt
	global_load_dwordx4 v[76:79], v[16:17], off offset:2048 nt
	global_load_dwordx4 v[64:67], v[16:17], off offset:3072 nt
	global_load_dwordx4 v[72:75], v[12:13], off offset:2048 nt
	global_load_dwordx4 v[24:27], v[12:13], off offset:3072 nt
	v_lshl_add_u64 v[12:13], v[108:109], 1, s[4:5]
	s_mov_b64 s[4:5], 0x1a1e4000
	v_and_b32_e32 v2, 64, v224
	v_lshl_add_u64 v[110:111], v[12:13], 0, s[4:5]
	v_add_u32_e32 v12, 64, v2
	v_xor_b32_e32 v2, 1, v224
	v_cmp_lt_i32_e32 vcc, v2, v12
	v_xor_b32_e32 v13, 2, v224
	s_mov_b32 s16, 0
	v_cndmask_b32_e32 v2, v224, v2, vcc
	v_cmp_lt_i32_e32 vcc, v13, v12
	v_lshlrev_b32_e32 v2, 2, v2
	s_nop 0
	v_cndmask_b32_e32 v13, v224, v13, vcc
	v_lshlrev_b32_e32 v112, 2, v13
	v_xor_b32_e32 v13, 4, v224
	v_cmp_lt_i32_e32 vcc, v13, v12
	s_nop 1
	v_cndmask_b32_e32 v13, v224, v13, vcc
	v_lshlrev_b32_e32 v113, 2, v13
	v_xor_b32_e32 v13, 8, v224
	v_cmp_lt_i32_e32 vcc, v13, v12
	s_nop 1
	v_cndmask_b32_e32 v13, v224, v13, vcc
	v_lshlrev_b32_e32 v114, 2, v13
	v_xor_b32_e32 v13, 16, v224
	v_cmp_lt_i32_e32 vcc, v13, v12
	s_nop 1
	v_cndmask_b32_e32 v13, v224, v13, vcc
	v_lshlrev_b32_e32 v115, 2, v13
	v_xor_b32_e32 v13, 32, v224
	v_cmp_lt_i32_e32 vcc, v13, v12
	s_nop 1
	v_cndmask_b32_e32 v12, v224, v13, vcc
	v_lshlrev_b32_e32 v116, 2, v12
	s_waitcnt vmcnt(0)
	s_branch .LBB0_909
.LBB0_908:
	v_lshlrev_b32_e32 v118, 16, v107
	v_and_b32_e32 v119, 0xffff0000, v107
	v_lshlrev_b32_e32 v124, 16, v106
	v_and_b32_e32 v125, 0xffff0000, v106
	v_lshlrev_b32_e32 v106, 16, v102
	v_and_b32_e32 v107, 0xffff0000, v102
	v_lshlrev_b32_e32 v120, 16, v103
	v_and_b32_e32 v121, 0xffff0000, v103
	v_pk_add_f32 v[102:103], v[106:107], v[124:125]
	v_and_b32_e32 v107, 0xffff0000, v86
	v_mul_f32_e32 v124, 0xbfb8aa3b, v107
	v_exp_f32_e32 v130, v124
	v_lshlrev_b32_e32 v124, 16, v105
	v_and_b32_e32 v125, 0xffff0000, v105
	v_lshlrev_b32_e32 v128, 16, v104
	v_and_b32_e32 v129, 0xffff0000, v104
	v_lshlrev_b32_e32 v104, 16, v100
	v_and_b32_e32 v105, 0xffff0000, v100
	v_lshlrev_b32_e32 v126, 16, v101
	v_and_b32_e32 v127, 0xffff0000, v101
	v_pk_add_f32 v[100:101], v[104:105], v[128:129]
	v_pk_add_f32 v[124:125], v[126:127], v[124:125]
	v_pk_mul_f32 v[104:105], v[100:101], v[100:101]
	v_pk_mul_f32 v[126:127], v[124:125], v[124:125]
	v_add_f32_e32 v104, v104, v105
	v_add_f32_e32 v104, v126, v104
	v_pk_add_f32 v[118:119], v[120:121], v[118:119]
	v_lshlrev_b32_e32 v120, 16, v87
	v_and_b32_e32 v121, 0xffff0000, v87
	v_lshlrev_b32_e32 v106, 16, v86
	v_pk_mul_f32 v[86:87], v[102:103], v[102:103]
	v_add_f32_e32 v104, v127, v104
	v_add_f32_e32 v86, v86, v104
	v_pk_mul_f32 v[122:123], v[118:119], v[118:119]
	v_add_f32_e32 v86, v87, v86
	v_add_f32_e32 v86, v122, v86
	v_add_f32_e32 v104, v123, v86
	v_mul_f32_e32 v117, 0xbfb8aa3b, v106
	ds_bpermute_b32 v105, v2, v104
	v_exp_f32_e32 v117, v117
	v_lshlrev_b32_e32 v126, 16, v84
	v_and_b32_e32 v127, 0xffff0000, v84
	v_add_f32_e32 v87, 1.0, v130
	v_add_f32_e32 v86, 1.0, v117
	s_waitcnt lgkmcnt(0)
	v_add_f32_e32 v117, v104, v105
	ds_bpermute_b32 v122, v112, v117
	v_lshlrev_b32_e32 v104, 16, v85
	v_mul_f32_e32 v105, 0xbfb8aa3b, v104
	v_exp_f32_e32 v123, v105
	v_and_b32_e32 v105, 0xffff0000, v85
	s_waitcnt lgkmcnt(0)
	v_add_f32_e32 v85, v117, v122
	ds_bpermute_b32 v117, v113, v85
	v_mul_f32_e32 v128, 0xbfb8aa3b, v127
	v_exp_f32_e32 v128, v128
	v_add_f32_e32 v122, 1.0, v123
	v_mul_f32_e32 v123, 0xbfb8aa3b, v105
	s_waitcnt lgkmcnt(0)
	v_add_f32_e32 v85, v85, v117
	ds_bpermute_b32 v117, v114, v85
	v_exp_f32_e32 v123, v123
	v_rcp_f32_e32 v122, v122
	v_rcp_f32_e32 v86, v86
	v_rcp_f32_e32 v87, v87
	s_waitcnt lgkmcnt(0)
	v_add_f32_e32 v84, v85, v117
	ds_bpermute_b32 v85, v115, v84
	v_mul_f32_e32 v117, 0xbfb8aa3b, v126
	v_exp_f32_e32 v117, v117
	v_add_f32_e32 v123, 1.0, v123
	v_rcp_f32_e32 v123, v123
	s_waitcnt lgkmcnt(0)
	v_add_f32_e32 v129, v84, v85
	ds_bpermute_b32 v130, v116, v129
	v_add_f32_e32 v84, 1.0, v117
	v_add_f32_e32 v85, 1.0, v128
	v_rcp_f32_e32 v84, v84
	v_rcp_f32_e32 v85, v85
	s_waitcnt lgkmcnt(0)
; DI unsigned pk2(float lo, float hi) { f32x2_t v = {lo, hi}; bf16x2_t b = __builtin_convertvector(v, bf16x2_t); return __builtin_bit_cast(unsigned, b); }
; DI float silu_f(float x) { return x * __builtin_amdgcn_rcpf(1.0f + __expf(-x)); }
; DI void phase_gla_post(const Frame& F0, const Args& a, int jl, int nrows) {
;     ...
;         for (int j = 0; j < 4; ++j) {
;             float o[8], r[8];
; #pragma unroll
;             for (int q = 0; q < 4; ++q) { o[2 * q] = bflo(of[j][q]) + bflo(ob[j][q]); o[2 * q + 1] = bfhi(of[j][q]) + bfhi(ob[j][q]); r[2 * q] = bflo(rr[j][q]); r[2 * q + 1] = bfhi(rr[j][q]); }
;             float ss = 0.f;
; #pragma unroll
;             for (int q = 0; q < 8; ++q) ss += o[q] * o[q];
;             const float rs = __builtin_amdgcn_rsqf(wave_sum(ss) * (1.0f / HV) + EPS);
;             float u[8];
; #pragma unroll
;             for (int q = 0; q < 8; ++q) { const float g = q < 4 ? g0[q] : g1[q - 4]; u[q] = o[q] * rs * g * silu_f(r[q]); }
;             wout[j] = (v4u){pk2(u[0], u[1]), pk2(u[2], u[3]), pk2(u[4], u[5]), pk2(u[6], u[7])};
	v_add_f32_e32 v117, v129, v130
	v_fmamk_f32 v117, v117, 0x3b000000, v223
	v_rsq_f32_e32 v128, v117
	v_pk_mul_f32 v[84:85], v[84:85], v[126:127]
	v_pk_mul_f32 v[104:105], v[122:123], v[104:105]
	v_pk_mul_f32 v[86:87], v[86:87], v[106:107]
	v_pk_mul_f32 v[100:101], v[100:101], v[128:129] op_sel_hi:[1,0]
	v_pk_mul_f32 v[102:103], v[102:103], v[128:129] op_sel_hi:[1,0]
	v_pk_mul_f32 v[100:101], v[4:5], v[100:101]
	v_pk_mul_f32 v[102:103], v[8:9], v[102:103]
	v_pk_mul_f32 v[84:85], v[84:85], v[100:101]
	v_pk_mul_f32 v[100:101], v[124:125], v[128:129] op_sel_hi:[1,0]
	v_pk_mul_f32 v[86:87], v[86:87], v[102:103]
	v_pk_mul_f32 v[100:101], v[6:7], v[100:101]
	v_pk_mul_f32 v[102:103], v[118:119], v[128:129] op_sel_hi:[1,0]
	v_pk_mul_f32 v[100:101], v[104:105], v[100:101]
	v_mul_f32_e32 v104, 0xbfb8aa3b, v120
	v_mul_f32_e32 v105, 0xbfb8aa3b, v121
	v_exp_f32_e32 v104, v104
	v_exp_f32_e32 v105, v105
	v_pk_mul_f32 v[102:103], v[10:11], v[102:103]
	v_cvt_pk_bf16_f32 v84, v84, v85
	v_add_f32_e32 v104, 1.0, v104
	v_add_f32_e32 v105, 1.0, v105
	v_rcp_f32_e32 v104, v104
	v_rcp_f32_e32 v105, v105
	v_cvt_pk_bf16_f32 v85, v100, v101
	v_lshlrev_b32_e32 v100, 16, v99
	v_and_b32_e32 v101, 0xffff0000, v99
	v_pk_mul_f32 v[104:105], v[104:105], v[120:121]
	v_lshlrev_b32_e32 v106, 16, v98
	v_pk_mul_f32 v[102:103], v[104:105], v[102:103]
	v_and_b32_e32 v107, 0xffff0000, v98
	v_lshlrev_b32_e32 v98, 16, v94
	v_and_b32_e32 v99, 0xffff0000, v94
	v_cvt_pk_bf16_f32 v86, v86, v87
	v_cvt_pk_bf16_f32 v87, v102, v103
	v_lshlrev_b32_e32 v102, 16, v95
	v_and_b32_e32 v103, 0xffff0000, v95
	v_pk_add_f32 v[94:95], v[98:99], v[106:107]
	v_lshlrev_b32_e32 v98, 16, v90
	v_and_b32_e32 v99, 0xffff0000, v90
	v_mul_f32_e32 v106, 0xbfb8aa3b, v98
	v_exp_f32_e32 v117, v106
	v_mul_f32_e32 v106, 0xbfb8aa3b, v99
	v_exp_f32_e32 v122, v106
	v_lshlrev_b32_e32 v106, 16, v97
	v_and_b32_e32 v107, 0xffff0000, v97
	v_lshlrev_b32_e32 v120, 16, v96
	v_and_b32_e32 v121, 0xffff0000, v96
	v_lshlrev_b32_e32 v96, 16, v92
	v_and_b32_e32 v97, 0xffff0000, v92
	v_lshlrev_b32_e32 v118, 16, v93
	v_and_b32_e32 v119, 0xffff0000, v93
	v_pk_add_f32 v[92:93], v[96:97], v[120:121]
	v_pk_add_f32 v[106:107], v[118:119], v[106:107]
	v_pk_mul_f32 v[96:97], v[92:93], v[92:93]
	v_pk_mul_f32 v[118:119], v[106:107], v[106:107]
	v_add_f32_e32 v96, v96, v97
	v_add_f32_e32 v96, v118, v96
	v_pk_add_f32 v[100:101], v[102:103], v[100:101]
	v_lshlrev_b32_e32 v102, 16, v91
	v_and_b32_e32 v103, 0xffff0000, v91
	v_pk_mul_f32 v[90:91], v[94:95], v[94:95]
	v_add_f32_e32 v96, v119, v96
	v_add_f32_e32 v90, v90, v96
	v_pk_mul_f32 v[104:105], v[100:101], v[100:101]
	v_add_f32_e32 v90, v91, v90
	v_add_f32_e32 v90, v104, v90
	v_add_f32_e32 v96, v105, v90
	ds_bpermute_b32 v97, v2, v96
	v_add_f32_e32 v90, 1.0, v117
	v_lshlrev_b32_e32 v118, 16, v88
	v_and_b32_e32 v119, 0xffff0000, v88
	v_add_f32_e32 v91, 1.0, v122
	s_waitcnt lgkmcnt(0)
	v_add_f32_e32 v104, v96, v97
	ds_bpermute_b32 v105, v112, v104
	v_lshlrev_b32_e32 v96, 16, v89
	v_mul_f32_e32 v97, 0xbfb8aa3b, v96
	v_exp_f32_e32 v117, v97
	v_and_b32_e32 v97, 0xffff0000, v89
	s_waitcnt lgkmcnt(0)
	v_add_f32_e32 v89, v104, v105
	ds_bpermute_b32 v105, v113, v89
	v_add_f32_e32 v104, 1.0, v117
	v_mul_f32_e32 v117, 0xbfb8aa3b, v97
	v_exp_f32_e32 v117, v117
	v_rcp_f32_e32 v104, v104
	s_waitcnt lgkmcnt(0)
	v_add_f32_e32 v89, v89, v105
	ds_bpermute_b32 v120, v114, v89
	v_add_f32_e32 v105, 1.0, v117
	v_mul_f32_e32 v117, 0xbfb8aa3b, v118
	v_exp_f32_e32 v117, v117
	v_rcp_f32_e32 v105, v105
	s_waitcnt lgkmcnt(0)
	v_add_f32_e32 v88, v89, v120
	ds_bpermute_b32 v89, v115, v88
	v_mul_f32_e32 v120, 0xbfb8aa3b, v119
	v_exp_f32_e32 v120, v120
	v_pk_mul_f32 v[96:97], v[104:105], v[96:97]
	v_rcp_f32_e32 v90, v90
	s_waitcnt lgkmcnt(0)
	v_add_f32_e32 v121, v88, v89
	ds_bpermute_b32 v122, v116, v121
	v_add_f32_e32 v88, 1.0, v117
	v_add_f32_e32 v89, 1.0, v120
	v_rcp_f32_e32 v88, v88
	v_rcp_f32_e32 v89, v89
	s_waitcnt lgkmcnt(0)
	v_add_f32_e32 v117, v121, v122
	v_fmamk_f32 v117, v117, 0x3b000000, v223
	v_rsq_f32_e32 v120, v117
	v_pk_mul_f32 v[88:89], v[88:89], v[118:119]
	v_rcp_f32_e32 v91, v91
	s_cmp_lt_i32 s16, s6
	v_pk_mul_f32 v[92:93], v[92:93], v[120:121] op_sel_hi:[1,0]
	v_pk_mul_f32 v[94:95], v[94:95], v[120:121] op_sel_hi:[1,0]
	v_pk_mul_f32 v[92:93], v[4:5], v[92:93]
	v_pk_mul_f32 v[90:91], v[90:91], v[98:99]
	v_pk_mul_f32 v[88:89], v[88:89], v[92:93]
	v_pk_mul_f32 v[92:93], v[106:107], v[120:121] op_sel_hi:[1,0]
	v_pk_mul_f32 v[94:95], v[8:9], v[94:95]
	v_pk_mul_f32 v[92:93], v[6:7], v[92:93]
	v_pk_mul_f32 v[90:91], v[90:91], v[94:95]
	v_pk_mul_f32 v[92:93], v[96:97], v[92:93]
	v_mul_f32_e32 v96, 0xbfb8aa3b, v102
	v_mul_f32_e32 v97, 0xbfb8aa3b, v103
	v_exp_f32_e32 v96, v96
	v_exp_f32_e32 v97, v97
	v_pk_mul_f32 v[94:95], v[100:101], v[120:121] op_sel_hi:[1,0]
	v_cvt_pk_bf16_f32 v88, v88, v89
	v_add_f32_e32 v96, 1.0, v96
	v_add_f32_e32 v97, 1.0, v97
	v_rcp_f32_e32 v96, v96
	v_rcp_f32_e32 v97, v97
	v_pk_mul_f32 v[94:95], v[10:11], v[94:95]
	v_cvt_pk_bf16_f32 v89, v92, v93
	v_lshlrev_b32_e32 v92, 16, v83
	v_pk_mul_f32 v[96:97], v[96:97], v[102:103]
	v_and_b32_e32 v93, 0xffff0000, v83
	v_pk_mul_f32 v[94:95], v[96:97], v[94:95]
	v_lshlrev_b32_e32 v98, 16, v82
	v_and_b32_e32 v99, 0xffff0000, v82
	v_lshlrev_b32_e32 v82, 16, v78
	v_and_b32_e32 v83, 0xffff0000, v78
	v_cvt_pk_bf16_f32 v90, v90, v91
	v_cvt_pk_bf16_f32 v91, v94, v95
	v_lshlrev_b32_e32 v94, 16, v79
	v_and_b32_e32 v95, 0xffff0000, v79
	v_pk_add_f32 v[78:79], v[82:83], v[98:99]
	v_lshlrev_b32_e32 v82, 16, v74
	v_and_b32_e32 v83, 0xffff0000, v74
	v_mul_f32_e32 v98, 0xbfb8aa3b, v82
	v_exp_f32_e32 v104, v98
	v_mul_f32_e32 v98, 0xbfb8aa3b, v83
	v_exp_f32_e32 v105, v98
	v_lshlrev_b32_e32 v98, 16, v81
	v_and_b32_e32 v99, 0xffff0000, v81
	v_lshlrev_b32_e32 v102, 16, v80
	v_and_b32_e32 v103, 0xffff0000, v80
	v_lshlrev_b32_e32 v80, 16, v76
	v_and_b32_e32 v81, 0xffff0000, v76
	v_lshlrev_b32_e32 v100, 16, v77
	v_and_b32_e32 v101, 0xffff0000, v77
	v_pk_add_f32 v[76:77], v[80:81], v[102:103]
	v_pk_add_f32 v[98:99], v[100:101], v[98:99]
	v_pk_mul_f32 v[80:81], v[76:77], v[76:77]
	v_pk_mul_f32 v[100:101], v[98:99], v[98:99]
	v_add_f32_e32 v80, v80, v81
	v_add_f32_e32 v80, v100, v80
	v_pk_add_f32 v[92:93], v[94:95], v[92:93]
	v_lshlrev_b32_e32 v94, 16, v75
	v_and_b32_e32 v95, 0xffff0000, v75
	v_pk_mul_f32 v[74:75], v[78:79], v[78:79]
	v_add_f32_e32 v80, v101, v80
	v_add_f32_e32 v74, v74, v80
	v_pk_mul_f32 v[96:97], v[92:93], v[92:93]
	v_add_f32_e32 v74, v75, v74
	v_add_f32_e32 v74, v96, v74
	v_add_f32_e32 v80, v97, v74
	ds_bpermute_b32 v81, v2, v80
	v_and_b32_e32 v101, 0xffff0000, v72
	v_add_f32_e32 v74, 1.0, v104
	v_add_f32_e32 v75, 1.0, v105
	v_mul_f32_e32 v103, 0xbfb8aa3b, v101
	s_waitcnt lgkmcnt(0)
; DI unsigned pk2(float lo, float hi) { f32x2_t v = {lo, hi}; bf16x2_t b = __builtin_convertvector(v, bf16x2_t); return __builtin_bit_cast(unsigned, b); }
; DI float silu_f(float x) { return x * __builtin_amdgcn_rcpf(1.0f + __expf(-x)); }
; DI void phase_gla_post(const Frame& F0, const Args& a, int jl, int nrows) {
;     ...
;         for (int j = 0; j < 4; ++j) {
;             float o[8], r[8];
; #pragma unroll
;             for (int q = 0; q < 4; ++q) { o[2 * q] = bflo(of[j][q]) + bflo(ob[j][q]); o[2 * q + 1] = bfhi(of[j][q]) + bfhi(ob[j][q]); r[2 * q] = bflo(rr[j][q]); r[2 * q + 1] = bfhi(rr[j][q]); }
;             float ss = 0.f;
; #pragma unroll
;             for (int q = 0; q < 8; ++q) ss += o[q] * o[q];
;             const float rs = __builtin_amdgcn_rsqf(wave_sum(ss) * (1.0f / HV) + EPS);
;             float u[8];
; #pragma unroll
;             for (int q = 0; q < 8; ++q) { const float g = q < 4 ? g0[q] : g1[q - 4]; u[q] = o[q] * rs * g * silu_f(r[q]); }
;             wout[j] = (v4u){pk2(u[0], u[1]), pk2(u[2], u[3]), pk2(u[4], u[5]), pk2(u[6], u[7])};
	v_add_f32_e32 v96, v80, v81
	ds_bpermute_b32 v97, v112, v96
	v_lshlrev_b32_e32 v80, 16, v73
	v_mul_f32_e32 v81, 0xbfb8aa3b, v80
	v_exp_f32_e32 v100, v81
	v_and_b32_e32 v81, 0xffff0000, v73
	s_waitcnt lgkmcnt(0)
	v_add_f32_e32 v73, v96, v97
	ds_bpermute_b32 v97, v113, v73
	v_add_f32_e32 v96, 1.0, v100
	v_mul_f32_e32 v100, 0xbfb8aa3b, v81
	v_exp_f32_e32 v100, v100
	v_exp_f32_e32 v103, v103
	s_waitcnt lgkmcnt(0)
	v_add_f32_e32 v73, v73, v97
	ds_bpermute_b32 v102, v114, v73
	v_add_f32_e32 v97, 1.0, v100
	v_lshlrev_b32_e32 v100, 16, v72
	v_rcp_f32_e32 v96, v96
	v_rcp_f32_e32 v97, v97
	s_waitcnt lgkmcnt(0)
	v_add_f32_e32 v72, v73, v102
	ds_bpermute_b32 v73, v115, v72
	v_mul_f32_e32 v102, 0xbfb8aa3b, v100
	v_exp_f32_e32 v102, v102
	v_pk_mul_f32 v[80:81], v[96:97], v[80:81]
	v_rcp_f32_e32 v74, v74
	s_waitcnt lgkmcnt(0)
	v_add_f32_e32 v104, v72, v73
	ds_bpermute_b32 v105, v116, v104
	v_add_f32_e32 v72, 1.0, v102
	v_add_f32_e32 v73, 1.0, v103
	v_rcp_f32_e32 v72, v72
	v_rcp_f32_e32 v73, v73
	s_waitcnt lgkmcnt(0)
	v_add_f32_e32 v102, v104, v105
	v_fmamk_f32 v102, v102, 0x3b000000, v223
	v_rsq_f32_e32 v102, v102
	v_pk_mul_f32 v[72:73], v[72:73], v[100:101]
	v_rcp_f32_e32 v75, v75
	s_cselect_b32 s46, s15, s12
	v_pk_mul_f32 v[76:77], v[76:77], v[102:103] op_sel_hi:[1,0]
	v_pk_mul_f32 v[78:79], v[78:79], v[102:103] op_sel_hi:[1,0]
	v_pk_mul_f32 v[76:77], v[4:5], v[76:77]
	v_pk_mul_f32 v[74:75], v[74:75], v[82:83]
	v_pk_mul_f32 v[72:73], v[72:73], v[76:77]
	v_pk_mul_f32 v[76:77], v[98:99], v[102:103] op_sel_hi:[1,0]
	v_pk_mul_f32 v[78:79], v[8:9], v[78:79]
	v_pk_mul_f32 v[76:77], v[6:7], v[76:77]
	v_pk_mul_f32 v[74:75], v[74:75], v[78:79]
	v_pk_mul_f32 v[76:77], v[80:81], v[76:77]
	v_mul_f32_e32 v80, 0xbfb8aa3b, v94
	v_mul_f32_e32 v81, 0xbfb8aa3b, v95
	v_exp_f32_e32 v80, v80
	v_exp_f32_e32 v81, v81
	v_pk_mul_f32 v[78:79], v[92:93], v[102:103] op_sel_hi:[1,0]
	v_cvt_pk_bf16_f32 v72, v72, v73
	v_add_f32_e32 v80, 1.0, v80
	v_add_f32_e32 v81, 1.0, v81
	v_rcp_f32_e32 v80, v80
	v_rcp_f32_e32 v81, v81
	v_pk_mul_f32 v[78:79], v[10:11], v[78:79]
	v_cvt_pk_bf16_f32 v73, v76, v77
	v_lshlrev_b32_e32 v76, 16, v71
	v_pk_mul_f32 v[80:81], v[80:81], v[94:95]
	v_and_b32_e32 v77, 0xffff0000, v71
	v_pk_mul_f32 v[78:79], v[80:81], v[78:79]
	v_lshlrev_b32_e32 v82, 16, v70
	v_and_b32_e32 v83, 0xffff0000, v70
	v_lshlrev_b32_e32 v70, 16, v66
	v_and_b32_e32 v71, 0xffff0000, v66
	v_cvt_pk_bf16_f32 v74, v74, v75
	v_cvt_pk_bf16_f32 v75, v78, v79
	v_lshlrev_b32_e32 v78, 16, v67
	v_and_b32_e32 v79, 0xffff0000, v67
	v_pk_add_f32 v[66:67], v[70:71], v[82:83]
	v_lshlrev_b32_e32 v70, 16, v26
	v_and_b32_e32 v71, 0xffff0000, v26
	v_mul_f32_e32 v82, 0xbfb8aa3b, v70
	v_exp_f32_e32 v96, v82
	v_mul_f32_e32 v82, 0xbfb8aa3b, v71
	v_exp_f32_e32 v97, v82
	v_lshlrev_b32_e32 v82, 16, v69
	v_and_b32_e32 v83, 0xffff0000, v69
	v_lshlrev_b32_e32 v94, 16, v68
	v_and_b32_e32 v95, 0xffff0000, v68
	v_lshlrev_b32_e32 v68, 16, v64
	v_and_b32_e32 v69, 0xffff0000, v64
	v_lshlrev_b32_e32 v92, 16, v65
	v_and_b32_e32 v93, 0xffff0000, v65
	v_pk_add_f32 v[64:65], v[68:69], v[94:95]
	v_pk_add_f32 v[82:83], v[92:93], v[82:83]
	v_pk_mul_f32 v[68:69], v[64:65], v[64:65]
	v_pk_mul_f32 v[92:93], v[82:83], v[82:83]
	v_add_f32_e32 v68, v68, v69
	v_add_f32_e32 v68, v92, v68
	v_pk_add_f32 v[76:77], v[78:79], v[76:77]
	v_lshlrev_b32_e32 v78, 16, v27
	v_and_b32_e32 v79, 0xffff0000, v27
	v_pk_mul_f32 v[26:27], v[66:67], v[66:67]
	v_add_f32_e32 v68, v93, v68
	v_add_f32_e32 v26, v26, v68
	v_pk_mul_f32 v[80:81], v[76:77], v[76:77]
	v_add_f32_e32 v26, v27, v26
	v_add_f32_e32 v26, v80, v26
	v_add_f32_e32 v68, v81, v26
	ds_bpermute_b32 v69, v2, v68
	v_and_b32_e32 v93, 0xffff0000, v24
	v_add_f32_e32 v26, 1.0, v96
	v_add_f32_e32 v27, 1.0, v97
	v_mul_f32_e32 v95, 0xbfb8aa3b, v93
	s_waitcnt lgkmcnt(0)
; #define GAS __attribute__((address_space(1)))
; DI unsigned pk2(float lo, float hi) { f32x2_t v = {lo, hi}; bf16x2_t b = __builtin_convertvector(v, bf16x2_t); return __builtin_bit_cast(unsigned, b); }
; DI float silu_f(float x) { return x * __builtin_amdgcn_rcpf(1.0f + __expf(-x)); }
; DI void phase_gla_post(const Frame& F0, const Args& a, int jl, int nrows) {
;     ...
;         for (int j = 0; j < 4; ++j) {
;             float o[8], r[8];
; #pragma unroll
;             for (int q = 0; q < 4; ++q) { o[2 * q] = bflo(of[j][q]) + bflo(ob[j][q]); o[2 * q + 1] = bfhi(of[j][q]) + bfhi(ob[j][q]); r[2 * q] = bflo(rr[j][q]); r[2 * q + 1] = bfhi(rr[j][q]); }
;             float ss = 0.f;
; #pragma unroll
;             for (int q = 0; q < 8; ++q) ss += o[q] * o[q];
;             const float rs = __builtin_amdgcn_rsqf(wave_sum(ss) * (1.0f / HV) + EPS);
;             float u[8];
; #pragma unroll
;             for (int q = 0; q < 8; ++q) { const float g = q < 4 ? g0[q] : g1[q - 4]; u[q] = o[q] * rs * g * silu_f(r[q]); }
;             wout[j] = (v4u){pk2(u[0], u[1]), pk2(u[2], u[3]), pk2(u[4], u[5]), pk2(u[6], u[7])};
;         }
; #pragma unroll
;         for (int j = 0; j < 4; ++j) *(GAS v4u*)(U + (size_t)R * VD + j * HV + F.lane * 8) = wout[j];
; #pragma unroll
;         for (int j = 0; j < 4; ++j) { of[j] = ofn[j]; ob[j] = obn[j]; rr[j] = rrn[j]; }
	v_add_f32_e32 v80, v68, v69
	ds_bpermute_b32 v81, v112, v80
	v_lshlrev_b32_e32 v68, 16, v25
	v_mul_f32_e32 v69, 0xbfb8aa3b, v68
	v_exp_f32_e32 v92, v69
	v_and_b32_e32 v69, 0xffff0000, v25
	s_waitcnt lgkmcnt(0)
	v_add_f32_e32 v25, v80, v81
	ds_bpermute_b32 v81, v113, v25
	v_add_f32_e32 v80, 1.0, v92
	v_mul_f32_e32 v92, 0xbfb8aa3b, v69
	v_exp_f32_e32 v92, v92
	v_exp_f32_e32 v95, v95
	s_waitcnt lgkmcnt(0)
	v_add_f32_e32 v25, v25, v81
	ds_bpermute_b32 v94, v114, v25
	v_add_f32_e32 v81, 1.0, v92
	v_lshlrev_b32_e32 v92, 16, v24
	v_rcp_f32_e32 v80, v80
	v_rcp_f32_e32 v81, v81
	s_waitcnt lgkmcnt(0)
	v_add_f32_e32 v24, v25, v94
	ds_bpermute_b32 v25, v115, v24
	v_mul_f32_e32 v94, 0xbfb8aa3b, v92
	v_exp_f32_e32 v94, v94
	v_pk_mul_f32 v[68:69], v[80:81], v[68:69]
	v_rcp_f32_e32 v26, v26
	s_waitcnt lgkmcnt(0)
	v_add_f32_e32 v96, v24, v25
	ds_bpermute_b32 v97, v116, v96
	v_add_f32_e32 v24, 1.0, v94
	v_add_f32_e32 v25, 1.0, v95
	v_rcp_f32_e32 v24, v24
	v_rcp_f32_e32 v25, v25
	s_waitcnt lgkmcnt(0)
	v_add_f32_e32 v94, v96, v97
	v_fmamk_f32 v94, v94, 0x3b000000, v223
	v_rsq_f32_e32 v94, v94
	v_pk_mul_f32 v[24:25], v[24:25], v[92:93]
	v_rcp_f32_e32 v27, v27
	s_ashr_i32 s47, s46, 31
	v_pk_mul_f32 v[64:65], v[64:65], v[94:95] op_sel_hi:[1,0]
	v_pk_mul_f32 v[66:67], v[66:67], v[94:95] op_sel_hi:[1,0]
	v_pk_mul_f32 v[64:65], v[4:5], v[64:65]
	v_pk_mul_f32 v[26:27], v[26:27], v[70:71]
	v_pk_mul_f32 v[24:25], v[24:25], v[64:65]
	v_pk_mul_f32 v[64:65], v[82:83], v[94:95] op_sel_hi:[1,0]
	v_pk_mul_f32 v[66:67], v[8:9], v[66:67]
	v_pk_mul_f32 v[64:65], v[6:7], v[64:65]
	v_pk_mul_f32 v[26:27], v[26:27], v[66:67]
	v_pk_mul_f32 v[64:65], v[68:69], v[64:65]
	v_mul_f32_e32 v68, 0xbfb8aa3b, v78
	v_mul_f32_e32 v69, 0xbfb8aa3b, v79
	v_exp_f32_e32 v68, v68
	v_exp_f32_e32 v69, v69
	v_pk_mul_f32 v[66:67], v[76:77], v[94:95] op_sel_hi:[1,0]
	s_lshl_b64 s[4:5], s[46:47], 12
	v_add_f32_e32 v68, 1.0, v68
	v_add_f32_e32 v69, 1.0, v69
	v_rcp_f32_e32 v68, v68
	v_rcp_f32_e32 v69, v69
	v_pk_mul_f32 v[66:67], v[10:11], v[66:67]
	v_cvt_pk_bf16_f32 v24, v24, v25
	v_cvt_pk_bf16_f32 v25, v64, v65
	v_pk_mul_f32 v[68:69], v[68:69], v[78:79]
	v_cvt_pk_bf16_f32 v26, v26, v27
	v_pk_mul_f32 v[66:67], v[68:69], v[66:67]
	v_lshl_add_u64 v[64:65], v[110:111], 0, s[4:5]
	v_cvt_pk_bf16_f32 v27, v66, v67
	global_store_dwordx4 v[64:65], v[84:87], off
	global_store_dwordx4 v[64:65], v[88:91], off offset:1024
	global_store_dwordx4 v[64:65], v[72:75], off offset:2048
	global_store_dwordx4 v[64:65], v[24:27], off offset:3072
	s_waitcnt vmcnt(4)
	v_mov_b64_e32 v[66:67], v[42:43]
	v_mov_b64_e32 v[78:79], v[46:47]
	v_mov_b64_e32 v[94:95], v[34:35]
	v_mov_b64_e32 v[102:103], v[38:39]
	v_mov_b64_e32 v[24:25], v[56:57]
	v_mov_b64_e32 v[74:75], v[62:63]
	v_mov_b64_e32 v[90:91], v[50:51]
	v_mov_b64_e32 v[86:87], v[54:55]
	v_mov_b64_e32 v[106:107], v[14:15]
	v_mov_b64_e32 v[98:99], v[18:19]
	v_mov_b64_e32 v[82:83], v[22:23]
	v_mov_b64_e32 v[70:71], v[30:31]
	s_cmp_lg_u32 s10, s13
	s_mov_b32 s15, s14
	v_mov_b64_e32 v[64:65], v[40:41]
	v_mov_b64_e32 v[76:77], v[44:45]
	v_mov_b64_e32 v[92:93], v[32:33]
	v_mov_b64_e32 v[100:101], v[36:37]
	v_mov_b64_e32 v[26:27], v[58:59]
	v_mov_b64_e32 v[72:73], v[60:61]
	v_mov_b64_e32 v[88:89], v[48:49]
	v_mov_b64_e32 v[84:85], v[52:53]
	v_mov_b64_e32 v[104:105], v[12:13]
	v_mov_b64_e32 v[96:97], v[16:17]
	v_mov_b64_e32 v[80:81], v[20:21]
	v_mov_b64_e32 v[68:69], v[28:29]
	s_mov_b32 s16, s13
	s_cbranch_scc0 .LBB0_905
